# P4: peel last K iteration, prefetch 7/16 residual tile loads into free VGPRs during it, epilogue regs swapped
# speedup vs baseline: 1.0204x; 1.0029x over previous
.LBB0_760:
	ds_read_b128 v[114:117], v232
	ds_read_b128 v[118:121], v232 offset:1024
	ds_read_b128 v[130:133], v232 offset:2048
	ds_read_b128 v[138:141], v232 offset:3072
	ds_read_b128 v[146:149], v233
	ds_read_b128 v[150:153], v233 offset:1024
	ds_read_b128 v[154:157], v233 offset:2048
	ds_read_b128 v[158:161], v233 offset:3072
	s_add_u32 s30, s28, 0xfffc0080
	s_addc_u32 s31, s29, -1
	s_cmp_eq_u32 s47, 12
	s_cselect_b32 s35, s3, s31
	s_cselect_b32 s34, s17, s30
	s_cselect_b32 s31, s19, s46
	s_cselect_b32 s30, s27, s45
	v_lshl_add_u64 v[206:207], s[28:29], 0, v[202:203]
	s_add_i32 m0, s36, 0xc000
	ds_read_b128 v[162:165], v234
	ds_read_b128 v[166:169], v234 offset:1024
	ds_read_b128 v[170:173], v234 offset:2048
	ds_read_b128 v[174:177], v234 offset:3072
	ds_read_b128 v[178:181], v234 offset:4096
	ds_read_b128 v[182:185], v234 offset:5120
	ds_read_b128 v[186:189], v234 offset:6144
	ds_read_b128 v[190:193], v234 offset:7168
	global_load_lds_dwordx4 v[206:207], off
	v_lshl_add_u64 v[206:207], s[28:29], 0, v[204:205]
	s_add_i32 m0, s36, 0xe000
	s_nop 0
	global_load_lds_dwordx4 v[206:207], off
	s_waitcnt vmcnt(8)
	s_waitcnt lgkmcnt(0)
	s_barrier
	s_setprio 1
	v_mfma_f32_16x16x32_bf16 v[142:145], v[114:117], v[162:165], v[142:145]
	v_mfma_f32_16x16x32_bf16 v[142:145], v[118:121], v[166:169], v[142:145]
	v_mfma_f32_16x16x32_bf16 v[134:137], v[130:133], v[162:165], v[134:137]
	v_mfma_f32_16x16x32_bf16 v[134:137], v[138:141], v[166:169], v[134:137]
	v_mfma_f32_16x16x32_bf16 v[106:109], v[130:133], v[170:173], v[106:109]
	v_mfma_f32_16x16x32_bf16 v[106:109], v[138:141], v[174:177], v[106:109]
	v_mfma_f32_16x16x32_bf16 v[110:113], v[114:117], v[170:173], v[110:113]
	v_mfma_f32_16x16x32_bf16 v[110:113], v[118:121], v[174:177], v[110:113]
	v_mfma_f32_16x16x32_bf16 v[94:97], v[114:117], v[178:181], v[94:97]
	v_mfma_f32_16x16x32_bf16 v[94:97], v[118:121], v[182:185], v[94:97]
	v_mfma_f32_16x16x32_bf16 v[90:93], v[130:133], v[178:181], v[90:93]
	v_mfma_f32_16x16x32_bf16 v[90:93], v[138:141], v[182:185], v[90:93]
	v_mfma_f32_16x16x32_bf16 v[74:77], v[130:133], v[186:189], v[74:77]
	v_mfma_f32_16x16x32_bf16 v[74:77], v[138:141], v[190:193], v[74:77]
	v_mfma_f32_16x16x32_bf16 v[78:81], v[114:117], v[186:189], v[78:81]
	v_mfma_f32_16x16x32_bf16 v[78:81], v[118:121], v[190:193], v[78:81]
	v_mfma_f32_16x16x32_bf16 v[126:129], v[146:149], v[162:165], v[126:129]
	v_mfma_f32_16x16x32_bf16 v[126:129], v[150:153], v[166:169], v[126:129]
	v_mfma_f32_16x16x32_bf16 v[122:125], v[154:157], v[162:165], v[122:125]
	v_mfma_f32_16x16x32_bf16 v[122:125], v[158:161], v[166:169], v[122:125]
	v_mfma_f32_16x16x32_bf16 v[98:101], v[154:157], v[170:173], v[98:101]
	v_mfma_f32_16x16x32_bf16 v[98:101], v[158:161], v[174:177], v[98:101]
	v_mfma_f32_16x16x32_bf16 v[102:105], v[146:149], v[170:173], v[102:105]
	v_mfma_f32_16x16x32_bf16 v[102:105], v[150:153], v[174:177], v[102:105]
	v_mfma_f32_16x16x32_bf16 v[86:89], v[146:149], v[178:181], v[86:89]
	v_mfma_f32_16x16x32_bf16 v[86:89], v[150:153], v[182:185], v[86:89]
	v_mfma_f32_16x16x32_bf16 v[82:85], v[154:157], v[178:181], v[82:85]
	v_mfma_f32_16x16x32_bf16 v[82:85], v[158:161], v[182:185], v[82:85]
	s_setprio 2
	s_barrier
	v_mfma_f32_16x16x32_bf16 v[66:69], v[154:157], v[186:189], v[66:69]
	v_mfma_f32_16x16x32_bf16 v[66:69], v[158:161], v[190:193], v[66:69]
	v_mfma_f32_16x16x32_bf16 v[70:73], v[146:149], v[186:189], v[70:73]
	v_mfma_f32_16x16x32_bf16 v[70:73], v[150:153], v[190:193], v[70:73]
	s_setprio 0
	s_nop 0
	s_add_i32 s48, s43, s33
	v_lshl_add_u64 v[206:207], s[30:31], 0, v[196:197]
	s_mov_b32 m0, s48
	ds_read_b128 v[162:165], v234 offset:16384
	ds_read_b128 v[166:169], v234 offset:17408
	ds_read_b128 v[170:173], v234 offset:18432
	ds_read_b128 v[174:177], v234 offset:19456
	ds_read_b128 v[178:181], v234 offset:20480
	ds_read_b128 v[182:185], v234 offset:21504
	ds_read_b128 v[186:189], v234 offset:22528
	ds_read_b128 v[190:193], v234 offset:23552
	global_load_lds_dwordx4 v[206:207], off
	s_add_i32 m0, s48, 0x2000
	s_add_u32 s48, s30, 0x40000
	v_lshl_add_u64 v[208:209], s[30:31], 0, v[200:201]
	s_addc_u32 s49, s31, 0
	s_add_i32 s50, s44, s33
	global_load_lds_dwordx4 v[208:209], off
	v_lshl_add_u64 v[210:211], s[48:49], 0, v[196:197]
	s_mov_b32 m0, s50
	v_lshl_add_u64 v[212:213], s[34:35], 0, v[198:199]
	global_load_lds_dwordx4 v[210:211], off
	v_lshl_add_u64 v[210:211], s[48:49], 0, v[200:201]
	s_add_i32 m0, s50, 0x2000
	s_nop 0
	global_load_lds_dwordx4 v[210:211], off
	v_lshl_add_u64 v[210:211], s[34:35], 0, v[194:195]
	s_mov_b32 m0, s36
	s_nop 0
	global_load_lds_dwordx4 v[210:211], off
	s_mov_b32 m0, s37
	s_nop 0
	global_load_lds_dwordx4 v[212:213], off
	s_waitcnt vmcnt(8)
	s_waitcnt lgkmcnt(0)
	s_barrier
	s_setprio 1
	v_mfma_f32_16x16x32_bf16 v[62:65], v[114:117], v[162:165], v[62:65]
	v_mfma_f32_16x16x32_bf16 v[62:65], v[118:121], v[166:169], v[62:65]
	v_mfma_f32_16x16x32_bf16 v[58:61], v[130:133], v[162:165], v[58:61]
	v_mfma_f32_16x16x32_bf16 v[58:61], v[138:141], v[166:169], v[58:61]
	v_mfma_f32_16x16x32_bf16 v[42:45], v[130:133], v[170:173], v[42:45]
	v_mfma_f32_16x16x32_bf16 v[42:45], v[138:141], v[174:177], v[42:45]
	v_mfma_f32_16x16x32_bf16 v[46:49], v[114:117], v[170:173], v[46:49]
	v_mfma_f32_16x16x32_bf16 v[46:49], v[118:121], v[174:177], v[46:49]
	v_mfma_f32_16x16x32_bf16 v[30:33], v[114:117], v[178:181], v[30:33]
	v_mfma_f32_16x16x32_bf16 v[30:33], v[118:121], v[182:185], v[30:33]
	v_mfma_f32_16x16x32_bf16 v[26:29], v[130:133], v[178:181], v[26:29]
	v_mfma_f32_16x16x32_bf16 v[26:29], v[138:141], v[182:185], v[26:29]
	v_mfma_f32_16x16x32_bf16 v[10:13], v[130:133], v[186:189], v[10:13]
	v_mfma_f32_16x16x32_bf16 v[10:13], v[138:141], v[190:193], v[10:13]
	v_mfma_f32_16x16x32_bf16 v[14:17], v[114:117], v[186:189], v[14:17]
	v_mfma_f32_16x16x32_bf16 v[14:17], v[118:121], v[190:193], v[14:17]
	v_mfma_f32_16x16x32_bf16 v[54:57], v[146:149], v[162:165], v[54:57]
	v_mfma_f32_16x16x32_bf16 v[54:57], v[150:153], v[166:169], v[54:57]
	v_mfma_f32_16x16x32_bf16 v[50:53], v[154:157], v[162:165], v[50:53]
	v_mfma_f32_16x16x32_bf16 v[50:53], v[158:161], v[166:169], v[50:53]
	v_mfma_f32_16x16x32_bf16 v[34:37], v[154:157], v[170:173], v[34:37]
	v_mfma_f32_16x16x32_bf16 v[34:37], v[158:161], v[174:177], v[34:37]
	v_mfma_f32_16x16x32_bf16 v[38:41], v[146:149], v[170:173], v[38:41]
	v_mfma_f32_16x16x32_bf16 v[38:41], v[150:153], v[174:177], v[38:41]
	v_mfma_f32_16x16x32_bf16 v[22:25], v[146:149], v[178:181], v[22:25]
	v_mfma_f32_16x16x32_bf16 v[22:25], v[150:153], v[182:185], v[22:25]
	v_mfma_f32_16x16x32_bf16 v[18:21], v[154:157], v[178:181], v[18:21]
	v_mfma_f32_16x16x32_bf16 v[18:21], v[158:161], v[182:185], v[18:21]
	s_setprio 2
	s_barrier
	v_mfma_f32_16x16x32_bf16 v[2:5], v[154:157], v[186:189], v[2:5]
	v_mfma_f32_16x16x32_bf16 v[2:5], v[158:161], v[190:193], v[2:5]
	v_mfma_f32_16x16x32_bf16 v[6:9], v[146:149], v[186:189], v[6:9]
	v_mfma_f32_16x16x32_bf16 v[6:9], v[150:153], v[190:193], v[6:9]
	s_setprio 0
	s_nop 0
	s_add_i32 s48, 0, 0x18000
	s_add_i32 s49, 0, 0x1c000
	v_add_u32_e32 v138, s48, v230
	v_add_u32_e32 v158, s49, v230
	ds_read_b128 v[114:117], v138
	ds_read_b128 v[118:121], v138 offset:1024
	ds_read_b128 v[130:133], v138 offset:2048
	ds_read_b128 v[138:141], v138 offset:3072
	ds_read_b128 v[146:149], v158
	ds_read_b128 v[150:153], v158 offset:1024
	ds_read_b128 v[154:157], v158 offset:2048
	ds_read_b128 v[158:161], v158 offset:3072
	s_add_u32 s34, s34, 0x40000
	s_addc_u32 s35, s35, 0
	s_mov_b32 m0, s38
	v_lshl_add_u64 v[214:215], s[34:35], 0, v[194:195]
	ds_read_b128 v[162:165], v234 offset:32768
	ds_read_b128 v[166:169], v234 offset:33792
	ds_read_b128 v[170:173], v234 offset:34816
	ds_read_b128 v[174:177], v234 offset:35840
	ds_read_b128 v[178:181], v234 offset:36864
	ds_read_b128 v[182:185], v234 offset:37888
	ds_read_b128 v[186:189], v234 offset:38912
	ds_read_b128 v[190:193], v234 offset:39936
	global_load_lds_dwordx4 v[214:215], off
	v_lshl_add_u64 v[214:215], s[34:35], 0, v[198:199]
	s_mov_b32 m0, s39
	s_nop 0
	global_load_lds_dwordx4 v[214:215], off
	s_waitcnt vmcnt(8)
	s_waitcnt lgkmcnt(0)
	s_barrier
	s_setprio 1
	v_mfma_f32_16x16x32_bf16 v[142:145], v[114:117], v[162:165], v[142:145]
	v_mfma_f32_16x16x32_bf16 v[142:145], v[118:121], v[166:169], v[142:145]
	v_mfma_f32_16x16x32_bf16 v[134:137], v[130:133], v[162:165], v[134:137]
	v_mfma_f32_16x16x32_bf16 v[134:137], v[138:141], v[166:169], v[134:137]
	v_mfma_f32_16x16x32_bf16 v[106:109], v[130:133], v[170:173], v[106:109]
	v_mfma_f32_16x16x32_bf16 v[106:109], v[138:141], v[174:177], v[106:109]
	v_mfma_f32_16x16x32_bf16 v[110:113], v[114:117], v[170:173], v[110:113]
	v_mfma_f32_16x16x32_bf16 v[110:113], v[118:121], v[174:177], v[110:113]
	v_mfma_f32_16x16x32_bf16 v[94:97], v[114:117], v[178:181], v[94:97]
	v_mfma_f32_16x16x32_bf16 v[94:97], v[118:121], v[182:185], v[94:97]
	v_mfma_f32_16x16x32_bf16 v[90:93], v[130:133], v[178:181], v[90:93]
	v_mfma_f32_16x16x32_bf16 v[90:93], v[138:141], v[182:185], v[90:93]
	v_mfma_f32_16x16x32_bf16 v[74:77], v[130:133], v[186:189], v[74:77]
	v_mfma_f32_16x16x32_bf16 v[74:77], v[138:141], v[190:193], v[74:77]
	v_mfma_f32_16x16x32_bf16 v[78:81], v[114:117], v[186:189], v[78:81]
	v_mfma_f32_16x16x32_bf16 v[78:81], v[118:121], v[190:193], v[78:81]
	v_mfma_f32_16x16x32_bf16 v[126:129], v[146:149], v[162:165], v[126:129]
	v_mfma_f32_16x16x32_bf16 v[126:129], v[150:153], v[166:169], v[126:129]
	v_mfma_f32_16x16x32_bf16 v[122:125], v[154:157], v[162:165], v[122:125]
	v_mfma_f32_16x16x32_bf16 v[122:125], v[158:161], v[166:169], v[122:125]
	v_mfma_f32_16x16x32_bf16 v[98:101], v[154:157], v[170:173], v[98:101]
	v_mfma_f32_16x16x32_bf16 v[98:101], v[158:161], v[174:177], v[98:101]
	v_mfma_f32_16x16x32_bf16 v[102:105], v[146:149], v[170:173], v[102:105]
	v_mfma_f32_16x16x32_bf16 v[102:105], v[150:153], v[174:177], v[102:105]
	v_mfma_f32_16x16x32_bf16 v[86:89], v[146:149], v[178:181], v[86:89]
	v_mfma_f32_16x16x32_bf16 v[86:89], v[150:153], v[182:185], v[86:89]
	v_mfma_f32_16x16x32_bf16 v[82:85], v[154:157], v[178:181], v[82:85]
	v_mfma_f32_16x16x32_bf16 v[82:85], v[158:161], v[182:185], v[82:85]
	s_setprio 2
	s_barrier
	v_mfma_f32_16x16x32_bf16 v[66:69], v[154:157], v[186:189], v[66:69]
	v_mfma_f32_16x16x32_bf16 v[66:69], v[158:161], v[190:193], v[66:69]
	v_mfma_f32_16x16x32_bf16 v[70:73], v[146:149], v[186:189], v[70:73]
	v_mfma_f32_16x16x32_bf16 v[70:73], v[150:153], v[190:193], v[70:73]
	s_setprio 0
	s_nop 0
	s_add_i32 s34, s48, s33
	v_lshl_add_u64 v[206:207], v[206:207], 0, s[8:9]
	s_mov_b32 m0, s34
	ds_read_b128 v[162:165], v234 offset:49152
	ds_read_b128 v[166:169], v234 offset:50176
	ds_read_b128 v[170:173], v234 offset:51200
	ds_read_b128 v[174:177], v234 offset:52224
	ds_read_b128 v[178:181], v234 offset:53248
	ds_read_b128 v[182:185], v234 offset:54272
	ds_read_b128 v[186:189], v234 offset:55296
	ds_read_b128 v[190:193], v234 offset:56320
	global_load_lds_dwordx4 v[206:207], off
	s_add_i32 m0, s34, 0x2000
	s_add_u32 s30, s30, 0x40080
	v_lshl_add_u64 v[206:207], v[208:209], 0, s[8:9]
	s_addc_u32 s31, s31, 0
	s_add_i32 s34, s49, s33
	global_load_lds_dwordx4 v[206:207], off
	v_lshl_add_u64 v[206:207], s[30:31], 0, v[196:197]
	s_mov_b32 m0, s34
	s_nop 0
	global_load_lds_dwordx4 v[206:207], off
	v_lshl_add_u64 v[206:207], s[30:31], 0, v[200:201]
	s_add_i32 m0, s34, 0x2000
	s_nop 0
	global_load_lds_dwordx4 v[206:207], off
	v_lshl_add_u64 v[206:207], v[210:211], 0, s[8:9]
	s_mov_b32 m0, s40
	s_nop 0
	global_load_lds_dwordx4 v[206:207], off
	v_lshl_add_u64 v[206:207], v[212:213], 0, s[8:9]
	s_mov_b32 m0, s41
	s_nop 0
	global_load_lds_dwordx4 v[206:207], off
	s_waitcnt vmcnt(8)
	s_waitcnt lgkmcnt(0)
	s_barrier
	s_setprio 1
	v_mfma_f32_16x16x32_bf16 v[62:65], v[114:117], v[162:165], v[62:65]
	v_mfma_f32_16x16x32_bf16 v[62:65], v[118:121], v[166:169], v[62:65]
	v_mfma_f32_16x16x32_bf16 v[58:61], v[130:133], v[162:165], v[58:61]
	v_mfma_f32_16x16x32_bf16 v[58:61], v[138:141], v[166:169], v[58:61]
	v_mfma_f32_16x16x32_bf16 v[42:45], v[130:133], v[170:173], v[42:45]
	v_mfma_f32_16x16x32_bf16 v[42:45], v[138:141], v[174:177], v[42:45]
	v_mfma_f32_16x16x32_bf16 v[46:49], v[114:117], v[170:173], v[46:49]
	v_mfma_f32_16x16x32_bf16 v[46:49], v[118:121], v[174:177], v[46:49]
	v_mfma_f32_16x16x32_bf16 v[30:33], v[114:117], v[178:181], v[30:33]
	v_mfma_f32_16x16x32_bf16 v[30:33], v[118:121], v[182:185], v[30:33]
	v_mfma_f32_16x16x32_bf16 v[26:29], v[130:133], v[178:181], v[26:29]
	v_mfma_f32_16x16x32_bf16 v[26:29], v[138:141], v[182:185], v[26:29]
	v_mfma_f32_16x16x32_bf16 v[10:13], v[130:133], v[186:189], v[10:13]
	v_mfma_f32_16x16x32_bf16 v[10:13], v[138:141], v[190:193], v[10:13]
	v_mfma_f32_16x16x32_bf16 v[14:17], v[114:117], v[186:189], v[14:17]
	v_mfma_f32_16x16x32_bf16 v[14:17], v[118:121], v[190:193], v[14:17]
	v_mfma_f32_16x16x32_bf16 v[54:57], v[146:149], v[162:165], v[54:57]
	v_mfma_f32_16x16x32_bf16 v[54:57], v[150:153], v[166:169], v[54:57]
	v_mfma_f32_16x16x32_bf16 v[50:53], v[154:157], v[162:165], v[50:53]
	v_mfma_f32_16x16x32_bf16 v[50:53], v[158:161], v[166:169], v[50:53]
	v_mfma_f32_16x16x32_bf16 v[34:37], v[154:157], v[170:173], v[34:37]
	v_mfma_f32_16x16x32_bf16 v[34:37], v[158:161], v[174:177], v[34:37]
	v_mfma_f32_16x16x32_bf16 v[38:41], v[146:149], v[170:173], v[38:41]
	v_mfma_f32_16x16x32_bf16 v[38:41], v[150:153], v[174:177], v[38:41]
	v_mfma_f32_16x16x32_bf16 v[22:25], v[146:149], v[178:181], v[22:25]
	v_mfma_f32_16x16x32_bf16 v[22:25], v[150:153], v[182:185], v[22:25]
	v_mfma_f32_16x16x32_bf16 v[18:21], v[154:157], v[178:181], v[18:21]
	v_mfma_f32_16x16x32_bf16 v[18:21], v[158:161], v[182:185], v[18:21]
	s_setprio 2
	s_barrier
	v_mfma_f32_16x16x32_bf16 v[2:5], v[154:157], v[186:189], v[2:5]
	v_mfma_f32_16x16x32_bf16 v[2:5], v[158:161], v[190:193], v[2:5]
	v_mfma_f32_16x16x32_bf16 v[6:9], v[146:149], v[186:189], v[6:9]
	v_mfma_f32_16x16x32_bf16 v[6:9], v[150:153], v[190:193], v[6:9]
	s_setprio 0
	s_nop 0
	s_add_i32 s47, s47, 2
	s_add_u32 s28, s28, 0x100
	s_addc_u32 s29, s29, 0
	s_add_u32 s45, s45, 0x100
	s_addc_u32 s46, s46, 0
	s_cmp_gt_u32 s47, 11
	s_cbranch_scc0 .LBB0_760
	s_lshl_b32 s86, s26, 9
	s_lshl_b32 s87, s2, 19
	s_add_u32 s86, s86, s87
	s_add_u32 s86, s84, s86
	s_addc_u32 s87, s85, 0
	s_add_u32 s88, s86, 0x8000
	s_addc_u32 s89, s87, 0
	s_add_u32 s90, s86, 0x10000
	s_addc_u32 s91, s87, 0
	s_add_u32 s92, s86, 0x18000
	s_addc_u32 s93, s87, 0
	v_lshlrev_b32_e32 v244, 11, v229
	v_lshl_add_u32 v244, v231, 1, v244
	ds_read_b128 v[114:117], v232
	ds_read_b128 v[118:121], v232 offset:1024
	ds_read_b128 v[130:133], v232 offset:2048
	ds_read_b128 v[138:141], v232 offset:3072
	ds_read_b128 v[146:149], v233
	ds_read_b128 v[150:153], v233 offset:1024
	ds_read_b128 v[154:157], v233 offset:2048
	ds_read_b128 v[158:161], v233 offset:3072
	s_add_u32 s30, s28, 0xfffc0080
	s_addc_u32 s31, s29, -1
	s_cmp_eq_u32 s47, 12
	s_cselect_b32 s35, s3, s31
	s_cselect_b32 s34, s17, s30
	s_cselect_b32 s31, s19, s46
	s_cselect_b32 s30, s27, s45
	v_lshl_add_u64 v[206:207], s[28:29], 0, v[202:203]
	s_add_i32 m0, s36, 0xc000
	ds_read_b128 v[162:165], v234
	ds_read_b128 v[166:169], v234 offset:1024
	ds_read_b128 v[170:173], v234 offset:2048
	ds_read_b128 v[174:177], v234 offset:3072
	ds_read_b128 v[178:181], v234 offset:4096
	ds_read_b128 v[182:185], v234 offset:5120
	ds_read_b128 v[186:189], v234 offset:6144
	ds_read_b128 v[190:193], v234 offset:7168
	global_load_lds_dwordx4 v[206:207], off
	v_lshl_add_u64 v[206:207], s[28:29], 0, v[204:205]
	s_add_i32 m0, s36, 0xe000
	s_nop 0
	global_load_lds_dwordx4 v[206:207], off
	global_load_dwordx4 v[216:219], v244, s[86:87]
	global_load_dwordx4 v[220:223], v244, s[86:87] offset:256
	global_load_dwordx4 v[224:227], v244, s[88:89]
	global_load_dwordx4 v[236:239], v244, s[88:89] offset:256
	global_load_dwordx4 v[240:243], v244, s[90:91]
	global_load_dwordx4 v[246:249], v244, s[90:91] offset:256
	global_load_dwordx4 v[250:253], v244, s[92:93]
	s_waitcnt vmcnt(15)
	s_waitcnt lgkmcnt(0)
	s_barrier
	s_setprio 1
	v_mfma_f32_16x16x32_bf16 v[142:145], v[114:117], v[162:165], v[142:145]
	v_mfma_f32_16x16x32_bf16 v[142:145], v[118:121], v[166:169], v[142:145]
	v_mfma_f32_16x16x32_bf16 v[134:137], v[130:133], v[162:165], v[134:137]
	v_mfma_f32_16x16x32_bf16 v[134:137], v[138:141], v[166:169], v[134:137]
	v_mfma_f32_16x16x32_bf16 v[106:109], v[130:133], v[170:173], v[106:109]
	v_mfma_f32_16x16x32_bf16 v[106:109], v[138:141], v[174:177], v[106:109]
	v_mfma_f32_16x16x32_bf16 v[110:113], v[114:117], v[170:173], v[110:113]
	v_mfma_f32_16x16x32_bf16 v[110:113], v[118:121], v[174:177], v[110:113]
	v_mfma_f32_16x16x32_bf16 v[94:97], v[114:117], v[178:181], v[94:97]
	v_mfma_f32_16x16x32_bf16 v[94:97], v[118:121], v[182:185], v[94:97]
	v_mfma_f32_16x16x32_bf16 v[90:93], v[130:133], v[178:181], v[90:93]
	v_mfma_f32_16x16x32_bf16 v[90:93], v[138:141], v[182:185], v[90:93]
	v_mfma_f32_16x16x32_bf16 v[74:77], v[130:133], v[186:189], v[74:77]
	v_mfma_f32_16x16x32_bf16 v[74:77], v[138:141], v[190:193], v[74:77]
	v_mfma_f32_16x16x32_bf16 v[78:81], v[114:117], v[186:189], v[78:81]
	v_mfma_f32_16x16x32_bf16 v[78:81], v[118:121], v[190:193], v[78:81]
	v_mfma_f32_16x16x32_bf16 v[126:129], v[146:149], v[162:165], v[126:129]
	v_mfma_f32_16x16x32_bf16 v[126:129], v[150:153], v[166:169], v[126:129]
	v_mfma_f32_16x16x32_bf16 v[122:125], v[154:157], v[162:165], v[122:125]
	v_mfma_f32_16x16x32_bf16 v[122:125], v[158:161], v[166:169], v[122:125]
	v_mfma_f32_16x16x32_bf16 v[98:101], v[154:157], v[170:173], v[98:101]
	v_mfma_f32_16x16x32_bf16 v[98:101], v[158:161], v[174:177], v[98:101]
	v_mfma_f32_16x16x32_bf16 v[102:105], v[146:149], v[170:173], v[102:105]
	v_mfma_f32_16x16x32_bf16 v[102:105], v[150:153], v[174:177], v[102:105]
	v_mfma_f32_16x16x32_bf16 v[86:89], v[146:149], v[178:181], v[86:89]
	v_mfma_f32_16x16x32_bf16 v[86:89], v[150:153], v[182:185], v[86:89]
	v_mfma_f32_16x16x32_bf16 v[82:85], v[154:157], v[178:181], v[82:85]
	v_mfma_f32_16x16x32_bf16 v[82:85], v[158:161], v[182:185], v[82:85]
	s_setprio 2
	s_barrier
	v_mfma_f32_16x16x32_bf16 v[66:69], v[154:157], v[186:189], v[66:69]
	v_mfma_f32_16x16x32_bf16 v[66:69], v[158:161], v[190:193], v[66:69]
	v_mfma_f32_16x16x32_bf16 v[70:73], v[146:149], v[186:189], v[70:73]
	v_mfma_f32_16x16x32_bf16 v[70:73], v[150:153], v[190:193], v[70:73]
	s_setprio 0
	s_nop 0
	s_add_i32 s48, s43, s33
	v_lshl_add_u64 v[206:207], s[30:31], 0, v[196:197]
	s_mov_b32 m0, s48
	ds_read_b128 v[162:165], v234 offset:16384
	ds_read_b128 v[166:169], v234 offset:17408
	ds_read_b128 v[170:173], v234 offset:18432
	ds_read_b128 v[174:177], v234 offset:19456
	ds_read_b128 v[178:181], v234 offset:20480
	ds_read_b128 v[182:185], v234 offset:21504
	ds_read_b128 v[186:189], v234 offset:22528
	ds_read_b128 v[190:193], v234 offset:23552
	global_load_lds_dwordx4 v[206:207], off
	s_add_i32 m0, s48, 0x2000
	s_add_u32 s48, s30, 0x40000
	v_lshl_add_u64 v[208:209], s[30:31], 0, v[200:201]
	s_addc_u32 s49, s31, 0
	s_add_i32 s50, s44, s33
	global_load_lds_dwordx4 v[208:209], off
	v_lshl_add_u64 v[210:211], s[48:49], 0, v[196:197]
	s_mov_b32 m0, s50
	v_lshl_add_u64 v[212:213], s[34:35], 0, v[198:199]
	global_load_lds_dwordx4 v[210:211], off
	v_lshl_add_u64 v[210:211], s[48:49], 0, v[200:201]
	s_add_i32 m0, s50, 0x2000
	s_nop 0
	global_load_lds_dwordx4 v[210:211], off
	v_lshl_add_u64 v[210:211], s[34:35], 0, v[194:195]
	s_mov_b32 m0, s36
	s_nop 0
	global_load_lds_dwordx4 v[210:211], off
	s_mov_b32 m0, s37
	s_nop 0
	global_load_lds_dwordx4 v[212:213], off
	s_waitcnt vmcnt(15)
	s_waitcnt lgkmcnt(0)
	s_barrier
	s_setprio 1
	v_mfma_f32_16x16x32_bf16 v[62:65], v[114:117], v[162:165], v[62:65]
	v_mfma_f32_16x16x32_bf16 v[62:65], v[118:121], v[166:169], v[62:65]
	v_mfma_f32_16x16x32_bf16 v[58:61], v[130:133], v[162:165], v[58:61]
	v_mfma_f32_16x16x32_bf16 v[58:61], v[138:141], v[166:169], v[58:61]
	v_mfma_f32_16x16x32_bf16 v[42:45], v[130:133], v[170:173], v[42:45]
	v_mfma_f32_16x16x32_bf16 v[42:45], v[138:141], v[174:177], v[42:45]
	v_mfma_f32_16x16x32_bf16 v[46:49], v[114:117], v[170:173], v[46:49]
	v_mfma_f32_16x16x32_bf16 v[46:49], v[118:121], v[174:177], v[46:49]
	v_mfma_f32_16x16x32_bf16 v[30:33], v[114:117], v[178:181], v[30:33]
	v_mfma_f32_16x16x32_bf16 v[30:33], v[118:121], v[182:185], v[30:33]
	v_mfma_f32_16x16x32_bf16 v[26:29], v[130:133], v[178:181], v[26:29]
	v_mfma_f32_16x16x32_bf16 v[26:29], v[138:141], v[182:185], v[26:29]
	v_mfma_f32_16x16x32_bf16 v[10:13], v[130:133], v[186:189], v[10:13]
	v_mfma_f32_16x16x32_bf16 v[10:13], v[138:141], v[190:193], v[10:13]
	v_mfma_f32_16x16x32_bf16 v[14:17], v[114:117], v[186:189], v[14:17]
	v_mfma_f32_16x16x32_bf16 v[14:17], v[118:121], v[190:193], v[14:17]
	v_mfma_f32_16x16x32_bf16 v[54:57], v[146:149], v[162:165], v[54:57]
	v_mfma_f32_16x16x32_bf16 v[54:57], v[150:153], v[166:169], v[54:57]
	v_mfma_f32_16x16x32_bf16 v[50:53], v[154:157], v[162:165], v[50:53]
	v_mfma_f32_16x16x32_bf16 v[50:53], v[158:161], v[166:169], v[50:53]
	v_mfma_f32_16x16x32_bf16 v[34:37], v[154:157], v[170:173], v[34:37]
	v_mfma_f32_16x16x32_bf16 v[34:37], v[158:161], v[174:177], v[34:37]
	v_mfma_f32_16x16x32_bf16 v[38:41], v[146:149], v[170:173], v[38:41]
	v_mfma_f32_16x16x32_bf16 v[38:41], v[150:153], v[174:177], v[38:41]
	v_mfma_f32_16x16x32_bf16 v[22:25], v[146:149], v[178:181], v[22:25]
	v_mfma_f32_16x16x32_bf16 v[22:25], v[150:153], v[182:185], v[22:25]
	v_mfma_f32_16x16x32_bf16 v[18:21], v[154:157], v[178:181], v[18:21]
	v_mfma_f32_16x16x32_bf16 v[18:21], v[158:161], v[182:185], v[18:21]
	s_setprio 2
	s_barrier
	v_mfma_f32_16x16x32_bf16 v[2:5], v[154:157], v[186:189], v[2:5]
	v_mfma_f32_16x16x32_bf16 v[2:5], v[158:161], v[190:193], v[2:5]
	v_mfma_f32_16x16x32_bf16 v[6:9], v[146:149], v[186:189], v[6:9]
	v_mfma_f32_16x16x32_bf16 v[6:9], v[150:153], v[190:193], v[6:9]
	s_setprio 0
	s_nop 0
	s_add_i32 s48, 0, 0x18000
	s_add_i32 s49, 0, 0x1c000
	v_add_u32_e32 v138, s48, v230
	v_add_u32_e32 v158, s49, v230
	ds_read_b128 v[114:117], v138
	ds_read_b128 v[118:121], v138 offset:1024
	ds_read_b128 v[130:133], v138 offset:2048
	ds_read_b128 v[138:141], v138 offset:3072
	ds_read_b128 v[146:149], v158
	ds_read_b128 v[150:153], v158 offset:1024
	ds_read_b128 v[154:157], v158 offset:2048
	ds_read_b128 v[158:161], v158 offset:3072
	s_add_u32 s34, s34, 0x40000
	s_addc_u32 s35, s35, 0
	s_mov_b32 m0, s38
	v_lshl_add_u64 v[214:215], s[34:35], 0, v[194:195]
	ds_read_b128 v[162:165], v234 offset:32768
	ds_read_b128 v[166:169], v234 offset:33792
	ds_read_b128 v[170:173], v234 offset:34816
	ds_read_b128 v[174:177], v234 offset:35840
	ds_read_b128 v[178:181], v234 offset:36864
	ds_read_b128 v[182:185], v234 offset:37888
	ds_read_b128 v[186:189], v234 offset:38912
	ds_read_b128 v[190:193], v234 offset:39936
	global_load_lds_dwordx4 v[214:215], off
	v_lshl_add_u64 v[214:215], s[34:35], 0, v[198:199]
	s_mov_b32 m0, s39
	s_nop 0
	global_load_lds_dwordx4 v[214:215], off
	s_waitcnt vmcnt(15)
	s_waitcnt lgkmcnt(0)
	s_barrier
	s_setprio 1
	v_mfma_f32_16x16x32_bf16 v[142:145], v[114:117], v[162:165], v[142:145]
	v_mfma_f32_16x16x32_bf16 v[142:145], v[118:121], v[166:169], v[142:145]
	v_mfma_f32_16x16x32_bf16 v[134:137], v[130:133], v[162:165], v[134:137]
	v_mfma_f32_16x16x32_bf16 v[134:137], v[138:141], v[166:169], v[134:137]
	v_mfma_f32_16x16x32_bf16 v[106:109], v[130:133], v[170:173], v[106:109]
	v_mfma_f32_16x16x32_bf16 v[106:109], v[138:141], v[174:177], v[106:109]
	v_mfma_f32_16x16x32_bf16 v[110:113], v[114:117], v[170:173], v[110:113]
	v_mfma_f32_16x16x32_bf16 v[110:113], v[118:121], v[174:177], v[110:113]
	v_mfma_f32_16x16x32_bf16 v[94:97], v[114:117], v[178:181], v[94:97]
	v_mfma_f32_16x16x32_bf16 v[94:97], v[118:121], v[182:185], v[94:97]
	v_mfma_f32_16x16x32_bf16 v[90:93], v[130:133], v[178:181], v[90:93]
	v_mfma_f32_16x16x32_bf16 v[90:93], v[138:141], v[182:185], v[90:93]
	v_mfma_f32_16x16x32_bf16 v[74:77], v[130:133], v[186:189], v[74:77]
	v_mfma_f32_16x16x32_bf16 v[74:77], v[138:141], v[190:193], v[74:77]
	v_mfma_f32_16x16x32_bf16 v[78:81], v[114:117], v[186:189], v[78:81]
	v_mfma_f32_16x16x32_bf16 v[78:81], v[118:121], v[190:193], v[78:81]
	v_mfma_f32_16x16x32_bf16 v[126:129], v[146:149], v[162:165], v[126:129]
	v_mfma_f32_16x16x32_bf16 v[126:129], v[150:153], v[166:169], v[126:129]
	v_mfma_f32_16x16x32_bf16 v[122:125], v[154:157], v[162:165], v[122:125]
	v_mfma_f32_16x16x32_bf16 v[122:125], v[158:161], v[166:169], v[122:125]
	v_mfma_f32_16x16x32_bf16 v[98:101], v[154:157], v[170:173], v[98:101]
	v_mfma_f32_16x16x32_bf16 v[98:101], v[158:161], v[174:177], v[98:101]
	v_mfma_f32_16x16x32_bf16 v[102:105], v[146:149], v[170:173], v[102:105]
	v_mfma_f32_16x16x32_bf16 v[102:105], v[150:153], v[174:177], v[102:105]
	v_mfma_f32_16x16x32_bf16 v[86:89], v[146:149], v[178:181], v[86:89]
	v_mfma_f32_16x16x32_bf16 v[86:89], v[150:153], v[182:185], v[86:89]
	v_mfma_f32_16x16x32_bf16 v[82:85], v[154:157], v[178:181], v[82:85]
	v_mfma_f32_16x16x32_bf16 v[82:85], v[158:161], v[182:185], v[82:85]
	s_setprio 2
	s_barrier
	v_mfma_f32_16x16x32_bf16 v[66:69], v[154:157], v[186:189], v[66:69]
	v_mfma_f32_16x16x32_bf16 v[66:69], v[158:161], v[190:193], v[66:69]
	v_mfma_f32_16x16x32_bf16 v[70:73], v[146:149], v[186:189], v[70:73]
	v_mfma_f32_16x16x32_bf16 v[70:73], v[150:153], v[190:193], v[70:73]
	s_setprio 0
	s_nop 0
	s_add_i32 s34, s48, s33
	v_lshl_add_u64 v[206:207], v[206:207], 0, s[8:9]
	s_mov_b32 m0, s34
	ds_read_b128 v[162:165], v234 offset:49152
	ds_read_b128 v[166:169], v234 offset:50176
	ds_read_b128 v[170:173], v234 offset:51200
	ds_read_b128 v[174:177], v234 offset:52224
	ds_read_b128 v[178:181], v234 offset:53248
	ds_read_b128 v[182:185], v234 offset:54272
	ds_read_b128 v[186:189], v234 offset:55296
	ds_read_b128 v[190:193], v234 offset:56320
	global_load_lds_dwordx4 v[206:207], off
	s_add_i32 m0, s34, 0x2000
	s_add_u32 s30, s30, 0x40080
	v_lshl_add_u64 v[206:207], v[208:209], 0, s[8:9]
	s_addc_u32 s31, s31, 0
	s_add_i32 s34, s49, s33
	global_load_lds_dwordx4 v[206:207], off
	v_lshl_add_u64 v[206:207], s[30:31], 0, v[196:197]
	s_mov_b32 m0, s34
	s_nop 0
	global_load_lds_dwordx4 v[206:207], off
	v_lshl_add_u64 v[206:207], s[30:31], 0, v[200:201]
	s_add_i32 m0, s34, 0x2000
	s_nop 0
	global_load_lds_dwordx4 v[206:207], off
	v_lshl_add_u64 v[206:207], v[210:211], 0, s[8:9]
	s_mov_b32 m0, s40
	s_nop 0
	global_load_lds_dwordx4 v[206:207], off
	v_lshl_add_u64 v[206:207], v[212:213], 0, s[8:9]
	s_mov_b32 m0, s41
	s_nop 0
	global_load_lds_dwordx4 v[206:207], off
	s_waitcnt vmcnt(21)
	s_waitcnt lgkmcnt(0)
	s_barrier
	s_setprio 1
	v_mfma_f32_16x16x32_bf16 v[62:65], v[114:117], v[162:165], v[62:65]
	v_mfma_f32_16x16x32_bf16 v[62:65], v[118:121], v[166:169], v[62:65]
	v_mfma_f32_16x16x32_bf16 v[58:61], v[130:133], v[162:165], v[58:61]
	v_mfma_f32_16x16x32_bf16 v[58:61], v[138:141], v[166:169], v[58:61]
	v_mfma_f32_16x16x32_bf16 v[42:45], v[130:133], v[170:173], v[42:45]
	v_mfma_f32_16x16x32_bf16 v[42:45], v[138:141], v[174:177], v[42:45]
	v_mfma_f32_16x16x32_bf16 v[46:49], v[114:117], v[170:173], v[46:49]
	v_mfma_f32_16x16x32_bf16 v[46:49], v[118:121], v[174:177], v[46:49]
	v_mfma_f32_16x16x32_bf16 v[30:33], v[114:117], v[178:181], v[30:33]
	v_mfma_f32_16x16x32_bf16 v[30:33], v[118:121], v[182:185], v[30:33]
	v_mfma_f32_16x16x32_bf16 v[26:29], v[130:133], v[178:181], v[26:29]
	v_mfma_f32_16x16x32_bf16 v[26:29], v[138:141], v[182:185], v[26:29]
	v_mfma_f32_16x16x32_bf16 v[10:13], v[130:133], v[186:189], v[10:13]
	v_mfma_f32_16x16x32_bf16 v[10:13], v[138:141], v[190:193], v[10:13]
	v_mfma_f32_16x16x32_bf16 v[14:17], v[114:117], v[186:189], v[14:17]
	v_mfma_f32_16x16x32_bf16 v[14:17], v[118:121], v[190:193], v[14:17]
	v_mfma_f32_16x16x32_bf16 v[54:57], v[146:149], v[162:165], v[54:57]
	v_mfma_f32_16x16x32_bf16 v[54:57], v[150:153], v[166:169], v[54:57]
	v_mfma_f32_16x16x32_bf16 v[50:53], v[154:157], v[162:165], v[50:53]
	v_mfma_f32_16x16x32_bf16 v[50:53], v[158:161], v[166:169], v[50:53]
	v_mfma_f32_16x16x32_bf16 v[34:37], v[154:157], v[170:173], v[34:37]
	v_mfma_f32_16x16x32_bf16 v[34:37], v[158:161], v[174:177], v[34:37]
	v_mfma_f32_16x16x32_bf16 v[38:41], v[146:149], v[170:173], v[38:41]
	v_mfma_f32_16x16x32_bf16 v[38:41], v[150:153], v[174:177], v[38:41]
	v_mfma_f32_16x16x32_bf16 v[22:25], v[146:149], v[178:181], v[22:25]
	v_mfma_f32_16x16x32_bf16 v[22:25], v[150:153], v[182:185], v[22:25]
	v_mfma_f32_16x16x32_bf16 v[18:21], v[154:157], v[178:181], v[18:21]
	v_mfma_f32_16x16x32_bf16 v[18:21], v[158:161], v[182:185], v[18:21]
	s_setprio 2
	s_barrier
	v_mfma_f32_16x16x32_bf16 v[2:5], v[154:157], v[186:189], v[2:5]
	v_mfma_f32_16x16x32_bf16 v[2:5], v[158:161], v[190:193], v[2:5]
	v_mfma_f32_16x16x32_bf16 v[6:9], v[146:149], v[186:189], v[6:9]
	v_mfma_f32_16x16x32_bf16 v[6:9], v[150:153], v[190:193], v[6:9]
	s_setprio 0
	s_nop 0
	s_add_i32 s47, s47, 2
	s_add_u32 s28, s28, 0x100
	s_addc_u32 s29, s29, 0
	s_add_u32 s45, s45, 0x100
	s_addc_u32 s46, s46, 0
	s_and_b64 vcc, exec, s[10:11]
	s_cbranch_vccz .LBB0_763
	s_barrier
.LBB0_763:
	s_and_b64 vcc, exec, s[12:13]
	s_cbranch_vccnz .Lp4pf_ok
	s_waitcnt vmcnt(0)
	v_mov_b32_e32 v216, 0
	v_mov_b32_e32 v217, 0
	v_mov_b32_e32 v218, 0
	v_mov_b32_e32 v219, 0
	v_mov_b32_e32 v220, 0
	v_mov_b32_e32 v221, 0
	v_mov_b32_e32 v222, 0
	v_mov_b32_e32 v223, 0
	v_mov_b32_e32 v224, 0
	v_mov_b32_e32 v225, 0
	v_mov_b32_e32 v226, 0
	v_mov_b32_e32 v227, 0
	v_mov_b32_e32 v236, 0
	v_mov_b32_e32 v237, 0
	v_mov_b32_e32 v238, 0
	v_mov_b32_e32 v239, 0
	v_mov_b32_e32 v240, 0
	v_mov_b32_e32 v241, 0
	v_mov_b32_e32 v242, 0
	v_mov_b32_e32 v243, 0
	v_mov_b32_e32 v246, 0
	v_mov_b32_e32 v247, 0
	v_mov_b32_e32 v248, 0
	v_mov_b32_e32 v249, 0
	v_mov_b32_e32 v250, 0
	v_mov_b32_e32 v251, 0
	v_mov_b32_e32 v252, 0
	v_mov_b32_e32 v253, 0
.Lp4pf_ok:
	v_lshl_or_b32 v206, s26, 8, v231
	v_lshl_add_u32 v188, s2, 8, v229
	v_ashrrev_i32_e32 v207, 31, v206
	v_ashrrev_i32_e32 v189, 31, v188
	v_lshl_add_u64 v[114:115], v[206:207], 1, s[84:85]
	v_lshlrev_b64 v[182:183], 11, v[188:189]
	v_cndmask_b32_e64 v118, 0, 1, s[12:13]
	v_lshl_add_u64 v[116:117], v[114:115], 0, v[182:183]
	v_cmp_ne_u32_e64 s[2:3], 1, v118
	s_andn2_b64 vcc, exec, s[12:13]
	s_cbranch_vccnz .LBB0_765
.LBB0_765:
	s_and_b64 vcc, exec, s[2:3]
	s_cbranch_vccnz .LBB0_767
.LBB0_767:
	v_or_b32_e32 v116, 16, v188
	v_ashrrev_i32_e32 v117, 31, v116
	v_lshlrev_b64 v[186:187], 11, v[116:117]
	v_lshl_add_u64 v[116:117], v[114:115], 0, v[186:187]
	s_and_b64 vcc, exec, s[2:3]
	s_cbranch_vccnz .LBB0_769

.LBB0_771:
	v_or_b32_e32 v116, 32, v188
	v_ashrrev_i32_e32 v117, 31, v116
	v_lshlrev_b64 v[192:193], 11, v[116:117]
	v_lshl_add_u64 v[116:117], v[114:115], 0, v[192:193]
	s_and_b64 vcc, exec, s[2:3]
	s_cbranch_vccnz .LBB0_773

.LBB0_775:
	v_or_b32_e32 v116, 48, v188
	v_ashrrev_i32_e32 v117, 31, v116
	v_lshlrev_b64 v[190:191], 11, v[116:117]
	v_lshl_add_u64 v[116:117], v[114:115], 0, v[190:191]
	v_mov_b32_e32 v162, 0
	s_and_b64 vcc, exec, s[2:3]
	s_cbranch_vccnz .LBB0_777

.LBB0_779:
	v_add_u32_e32 v116, 0x80, v188
	v_ashrrev_i32_e32 v117, 31, v116
	v_lshlrev_b64 v[214:215], 11, v[116:117]
	v_lshl_add_u64 v[116:117], v[114:115], 0, v[214:215]
	v_mov_b32_e32 v154, 0
	s_and_b64 vcc, exec, s[2:3]
	v_mov_b32_e32 v158, 0
	v_mov_b32_e32 v159, 0
	v_mov_b32_e32 v160, 0
	v_mov_b32_e32 v161, 0
	s_cbranch_vccnz .LBB0_781
	global_load_dwordx4 v[158:161], v[116:117], off

.LBB0_783:
	v_add_u32_e32 v116, 0x90, v188
	v_ashrrev_i32_e32 v117, 31, v116
	v_lshlrev_b64 v[212:213], 11, v[116:117]
	v_lshl_add_u64 v[116:117], v[114:115], 0, v[212:213]
	v_mov_b32_e32 v146, 0
	s_and_b64 vcc, exec, s[2:3]
	v_mov_b32_e32 v150, 0
	v_mov_b32_e32 v151, 0
	v_mov_b32_e32 v152, 0
	v_mov_b32_e32 v153, 0
	s_cbranch_vccnz .LBB0_785
	global_load_dwordx4 v[150:153], v[116:117], off

.LBB0_787:
	v_add_u32_e32 v116, 0xa0, v188
	v_ashrrev_i32_e32 v117, 31, v116
	v_lshlrev_b64 v[210:211], 11, v[116:117]
	v_lshl_add_u64 v[116:117], v[114:115], 0, v[210:211]
	v_mov_b32_e32 v130, 0
	s_and_b64 vcc, exec, s[2:3]
	v_mov_b32_e32 v138, 0
	v_mov_b32_e32 v139, 0
	v_mov_b32_e32 v140, 0
	v_mov_b32_e32 v141, 0
	s_cbranch_vccnz .LBB0_789
	global_load_dwordx4 v[138:141], v[116:117], off

.LBB0_791:
	v_add_u32_e32 v116, 0xb0, v188
	v_ashrrev_i32_e32 v117, 31, v116
	v_lshlrev_b64 v[208:209], 11, v[116:117]
	v_lshl_add_u64 v[184:185], v[114:115], 0, v[208:209]
	v_mov_b32_e32 v114, 0
	s_and_b64 vcc, exec, s[2:3]
	v_mov_b32_e32 v118, 0
	v_mov_b32_e32 v119, 0
	v_mov_b32_e32 v120, 0
	v_mov_b32_e32 v121, 0
	s_cbranch_vccnz .LBB0_793
	global_load_dwordx4 v[118:121], v[184:185], off
.LBB0_793:
	s_and_b64 vcc, exec, s[2:3]
	v_mov_b32_e32 v115, 0
	v_mov_b32_e32 v116, 0
	v_mov_b32_e32 v117, 0
	s_cbranch_vccnz .LBB0_795
	global_load_dwordx4 v[114:117], v[184:185], off offset:256
.LBB0_795:
	s_waitcnt vmcnt(0)
	v_lshlrev_b32_e32 v184, 16, v216
	v_and_b32_e32 v185, 0xffff0000, v216
	v_lshlrev_b32_e32 v216, 16, v217
	v_and_b32_e32 v217, 0xffff0000, v217
	v_pk_add_f32 v[144:145], v[144:145], v[216:217]
	v_pk_add_f32 v[216:217], v[142:143], v[184:185]
	v_lshlrev_b32_e32 v184, 16, v218
	v_and_b32_e32 v185, 0xffff0000, v218
	v_lshlrev_b32_e32 v142, 16, v219
	v_and_b32_e32 v143, 0xffff0000, v219
	v_pk_add_f32 v[142:143], v[136:137], v[142:143]
	v_pk_add_f32 v[218:219], v[134:135], v[184:185]
	s_mov_b64 s[2:3], -1
	s_and_b64 vcc, exec, s[14:15]
	v_cvt_pk_bf16_f32 v134, v216, v217
	v_cvt_pk_bf16_f32 v135, v144, v145
	v_cvt_pk_bf16_f32 v136, v218, v219
	v_cvt_pk_bf16_f32 v137, v142, v143
	s_cbranch_vccz .LBB0_797
	s_mov_b64 s[2:3], 0
.LBB0_797:
	v_lshl_add_u64 v[182:183], s[64:65], 0, v[182:183]
	s_andn2_b64 vcc, exec, s[2:3]
	v_lshl_add_u64 v[182:183], v[206:207], 1, v[182:183]
	s_cbranch_vccnz .LBB0_799
	global_store_dwordx4 v[182:183], v[134:137], off
.LBB0_799:
	s_nop 1
	v_lshlrev_b32_e32 v134, 16, v220
	v_and_b32_e32 v135, 0xffff0000, v220
	v_lshlrev_b32_e32 v136, 16, v221
	v_and_b32_e32 v137, 0xffff0000, v221
	v_pk_add_f32 v[128:129], v[128:129], v[136:137]
	v_pk_add_f32 v[134:135], v[126:127], v[134:135]
	v_lshlrev_b32_e32 v136, 16, v222
	v_and_b32_e32 v137, 0xffff0000, v222
	v_lshlrev_b32_e32 v126, 16, v223
	v_and_b32_e32 v127, 0xffff0000, v223
	v_cndmask_b32_e64 v220, 0, 1, s[14:15]
	v_pk_add_f32 v[126:127], v[124:125], v[126:127]
	v_pk_add_f32 v[136:137], v[122:123], v[136:137]
	v_cmp_ne_u32_e64 s[2:3], 1, v220
	s_andn2_b64 vcc, exec, s[14:15]
	s_mov_b64 s[26:27], -1
	v_cvt_pk_bf16_f32 v122, v134, v135
	v_cvt_pk_bf16_f32 v123, v128, v129
	v_cvt_pk_bf16_f32 v124, v136, v137
	v_cvt_pk_bf16_f32 v125, v126, v127
	s_cbranch_vccnz .LBB0_801
	s_mov_b64 s[26:27], 0
.LBB0_801:
	s_andn2_b64 vcc, exec, s[26:27]
	s_cbranch_vccnz .LBB0_803
	global_store_dwordx4 v[182:183], v[122:125], off offset:256
.LBB0_803:
	s_nop 1
	v_mul_f32_e32 v122, v217, v217
	v_mul_f32_e32 v123, v145, v145
	v_fmac_f32_e32 v122, v216, v216
	v_fmac_f32_e32 v123, v144, v144
	v_add_f32_e32 v122, v122, v123
	v_mul_f32_e32 v123, v219, v219
	v_mul_f32_e32 v124, v143, v143
	v_fmac_f32_e32 v123, v218, v218
	v_fmac_f32_e32 v124, v142, v142
	v_add_f32_e32 v123, v123, v124
	v_add_f32_e32 v122, v122, v123
	v_mul_f32_e32 v123, v135, v135
	v_mul_f32_e32 v124, v129, v129
	v_fmac_f32_e32 v123, v134, v134
	v_fmac_f32_e32 v124, v128, v128
	v_add_f32_e32 v123, v123, v124
	v_mul_f32_e32 v124, v137, v137
	v_mul_f32_e32 v125, v127, v127
	v_fmac_f32_e32 v124, v136, v136
	v_fmac_f32_e32 v125, v126, v126
	v_add_f32_e32 v124, v124, v125
	v_add_f32_e32 v123, v123, v124
	v_and_b32_e32 v124, 64, v235
	v_add_f32_e32 v122, v122, v123
	v_xor_b32_e32 v123, 16, v235
	v_add_u32_e32 v125, 64, v124
	v_cmp_lt_i32_e32 vcc, v123, v125
	s_nop 1
	v_cndmask_b32_e32 v123, v235, v123, vcc
	v_lshlrev_b32_e32 v134, 2, v123
	ds_bpermute_b32 v123, v134, v122
	s_waitcnt lgkmcnt(0)
	v_add_f32_e32 v124, v122, v123
	v_xor_b32_e32 v122, 32, v235
	v_cmp_lt_i32_e32 vcc, v122, v125
	s_nop 1
	v_cndmask_b32_e32 v122, v235, v122, vcc
	v_lshlrev_b32_e32 v135, 2, v122
	ds_bpermute_b32 v125, v135, v124
	v_lshl_add_u64 v[122:123], v[188:189], 2, s[4:5]
	s_and_saveexec_b64 s[26:27], s[0:1]
	s_cbranch_execz .LBB0_805
	s_waitcnt lgkmcnt(0)
	v_add_f32_e32 v124, v124, v125
	global_atomic_add_f32 v[122:123], v124, off
.LBB0_805:
	s_or_b64 exec, exec, s[26:27]
	v_lshlrev_b32_e32 v124, 16, v224
	s_waitcnt lgkmcnt(0)
	v_and_b32_e32 v125, 0xffff0000, v224
	v_lshlrev_b32_e32 v126, 16, v225
	v_and_b32_e32 v127, 0xffff0000, v225
	v_pk_add_f32 v[112:113], v[112:113], v[126:127]
	v_pk_add_f32 v[124:125], v[110:111], v[124:125]
	v_lshlrev_b32_e32 v126, 16, v226
	v_and_b32_e32 v127, 0xffff0000, v226
	v_lshlrev_b32_e32 v110, 16, v227
	v_and_b32_e32 v111, 0xffff0000, v227
	v_pk_add_f32 v[110:111], v[108:109], v[110:111]
	v_pk_add_f32 v[126:127], v[106:107], v[126:127]
	s_and_b64 vcc, exec, s[2:3]
	s_mov_b64 s[26:27], -1
	v_cvt_pk_bf16_f32 v106, v124, v125
	v_cvt_pk_bf16_f32 v107, v112, v113
	v_cvt_pk_bf16_f32 v108, v126, v127
	v_cvt_pk_bf16_f32 v109, v110, v111
	s_cbranch_vccnz .LBB0_807
	s_mov_b64 s[26:27], 0
.LBB0_807:
	v_lshl_add_u64 v[128:129], s[64:65], 0, v[186:187]
	s_andn2_b64 vcc, exec, s[26:27]
	v_lshl_add_u64 v[128:129], v[206:207], 1, v[128:129]
	s_cbranch_vccnz .LBB0_809
	global_store_dwordx4 v[128:129], v[106:109], off
.LBB0_809:
	s_nop 1
	v_lshlrev_b32_e32 v106, 16, v236
	v_and_b32_e32 v107, 0xffff0000, v236
	v_lshlrev_b32_e32 v108, 16, v237
	v_and_b32_e32 v109, 0xffff0000, v237
	v_pk_add_f32 v[104:105], v[104:105], v[108:109]
	v_pk_add_f32 v[106:107], v[102:103], v[106:107]
	v_lshlrev_b32_e32 v108, 16, v238
	v_and_b32_e32 v109, 0xffff0000, v238
	v_lshlrev_b32_e32 v102, 16, v239
	v_and_b32_e32 v103, 0xffff0000, v239
	v_pk_add_f32 v[102:103], v[100:101], v[102:103]
	v_pk_add_f32 v[108:109], v[98:99], v[108:109]
	s_and_b64 vcc, exec, s[2:3]
	s_mov_b64 s[26:27], -1
	v_cvt_pk_bf16_f32 v98, v106, v107
	v_cvt_pk_bf16_f32 v99, v104, v105
	v_cvt_pk_bf16_f32 v100, v108, v109
	v_cvt_pk_bf16_f32 v101, v102, v103
	s_cbranch_vccnz .LBB0_811
	s_mov_b64 s[26:27], 0

.LBB0_815:
	s_or_b64 exec, exec, s[26:27]
	v_lshlrev_b32_e32 v98, 16, v240
	s_waitcnt lgkmcnt(0)
	v_and_b32_e32 v99, 0xffff0000, v240
	v_lshlrev_b32_e32 v100, 16, v241
	v_and_b32_e32 v101, 0xffff0000, v241
	v_pk_add_f32 v[96:97], v[96:97], v[100:101]
	v_pk_add_f32 v[98:99], v[94:95], v[98:99]
	v_lshlrev_b32_e32 v100, 16, v242
	v_and_b32_e32 v101, 0xffff0000, v242
	v_lshlrev_b32_e32 v94, 16, v243
	v_and_b32_e32 v95, 0xffff0000, v243
	v_pk_add_f32 v[94:95], v[92:93], v[94:95]
	v_pk_add_f32 v[100:101], v[90:91], v[100:101]
	s_and_b64 vcc, exec, s[2:3]
	s_mov_b64 s[26:27], -1
	v_cvt_pk_bf16_f32 v90, v98, v99
	v_cvt_pk_bf16_f32 v91, v96, v97
	v_cvt_pk_bf16_f32 v92, v100, v101
	v_cvt_pk_bf16_f32 v93, v94, v95
	s_cbranch_vccnz .LBB0_817
	s_mov_b64 s[26:27], 0
.LBB0_817:
	v_lshl_add_u64 v[102:103], s[64:65], 0, v[192:193]
	s_andn2_b64 vcc, exec, s[26:27]
	v_lshl_add_u64 v[102:103], v[206:207], 1, v[102:103]
	s_cbranch_vccnz .LBB0_819
	global_store_dwordx4 v[102:103], v[90:93], off
.LBB0_819:
	s_nop 1
	v_lshlrev_b32_e32 v90, 16, v246
	v_and_b32_e32 v91, 0xffff0000, v246
	v_lshlrev_b32_e32 v92, 16, v247
	v_and_b32_e32 v93, 0xffff0000, v247
	v_pk_add_f32 v[88:89], v[88:89], v[92:93]
	v_pk_add_f32 v[90:91], v[86:87], v[90:91]
	v_lshlrev_b32_e32 v92, 16, v248
	v_and_b32_e32 v93, 0xffff0000, v248
	v_lshlrev_b32_e32 v86, 16, v249
	v_and_b32_e32 v87, 0xffff0000, v249
	v_pk_add_f32 v[86:87], v[84:85], v[86:87]
	v_pk_add_f32 v[92:93], v[82:83], v[92:93]
	s_and_b64 vcc, exec, s[2:3]
	s_mov_b64 s[26:27], -1
	v_cvt_pk_bf16_f32 v82, v90, v91
	v_cvt_pk_bf16_f32 v83, v88, v89
	v_cvt_pk_bf16_f32 v84, v92, v93
	v_cvt_pk_bf16_f32 v85, v86, v87
	s_cbranch_vccnz .LBB0_821
	s_mov_b64 s[26:27], 0

.LBB0_825:
	s_or_b64 exec, exec, s[26:27]
	v_lshlrev_b32_e32 v82, 16, v250
	s_waitcnt lgkmcnt(0)
	v_and_b32_e32 v83, 0xffff0000, v250
	v_lshlrev_b32_e32 v84, 16, v251
	v_and_b32_e32 v85, 0xffff0000, v251
	v_pk_add_f32 v[80:81], v[80:81], v[84:85]
	v_pk_add_f32 v[82:83], v[78:79], v[82:83]
	v_lshlrev_b32_e32 v84, 16, v252
	v_and_b32_e32 v85, 0xffff0000, v252
	v_lshlrev_b32_e32 v78, 16, v253
	v_and_b32_e32 v79, 0xffff0000, v253
	v_pk_add_f32 v[78:79], v[76:77], v[78:79]
	v_pk_add_f32 v[84:85], v[74:75], v[84:85]
	s_and_b64 vcc, exec, s[2:3]
	s_mov_b64 s[26:27], -1
	v_cvt_pk_bf16_f32 v74, v82, v83
	v_cvt_pk_bf16_f32 v75, v80, v81
	v_cvt_pk_bf16_f32 v76, v84, v85
	v_cvt_pk_bf16_f32 v77, v78, v79
	s_cbranch_vccnz .LBB0_827
	s_mov_b64 s[26:27], 0
.LBB0_827:
	v_lshl_add_u64 v[86:87], s[64:65], 0, v[190:191]
	s_andn2_b64 vcc, exec, s[26:27]
	v_lshl_add_u64 v[86:87], v[206:207], 1, v[86:87]
	s_cbranch_vccnz .LBB0_829
	global_store_dwordx4 v[86:87], v[74:77], off

	.amdhsa_kernel _Z8fwd_mega4Args
		.amdhsa_group_segment_fixed_size 0
		.amdhsa_private_segment_fixed_size 0
		.amdhsa_kernarg_size 160
		.amdhsa_user_sgpr_count 2
		.amdhsa_user_sgpr_dispatch_ptr 0
		.amdhsa_user_sgpr_queue_ptr 0
		.amdhsa_user_sgpr_kernarg_segment_ptr 1
		.amdhsa_user_sgpr_dispatch_id 0
		.amdhsa_user_sgpr_kernarg_preload_length 0
		.amdhsa_user_sgpr_kernarg_preload_offset 0
		.amdhsa_user_sgpr_private_segment_size 0
		.amdhsa_uses_dynamic_stack 0
		.amdhsa_enable_private_segment 0
		.amdhsa_system_sgpr_workgroup_id_x 1
		.amdhsa_system_sgpr_workgroup_id_y 0
		.amdhsa_system_sgpr_workgroup_id_z 0
		.amdhsa_system_sgpr_workgroup_info 0
		.amdhsa_system_vgpr_workitem_id 0
		.amdhsa_next_free_vgpr 256
		.amdhsa_next_free_sgpr 98
		.amdhsa_accum_offset 256
		.amdhsa_reserve_vcc 1
		.amdhsa_float_round_mode_32 0
		.amdhsa_float_round_mode_16_64 0
		.amdhsa_float_denorm_mode_32 3
		.amdhsa_float_denorm_mode_16_64 3
		.amdhsa_dx10_clamp 1
		.amdhsa_ieee_mode 1
		.amdhsa_fp16_overflow 0
		.amdhsa_tg_split 0
		.amdhsa_exception_fp_ieee_invalid_op 0
		.amdhsa_exception_fp_denorm_src 0
		.amdhsa_exception_fp_ieee_div_zero 0
		.amdhsa_exception_fp_ieee_overflow 0
		.amdhsa_exception_fp_ieee_underflow 0
		.amdhsa_exception_fp_ieee_inexact 0
		.amdhsa_exception_int_div_zero 0
	.end_amdhsa_kernel

amdhsa.kernels:
  - .agpr_count:     0
    .args:
      - .offset:         0
        .size:           160
        .value_kind:     by_value
    .group_segment_fixed_size: 0
    .kernarg_segment_align: 8
    .kernarg_segment_size: 160
    .language:       OpenCL C
    .language_version:
      - 2
      - 0
    .max_flat_workgroup_size: 512
    .name:           _Z8fwd_mega4Args
    .private_segment_fixed_size: 0
    .sgpr_count:     104
    .sgpr_spill_count: 56
    .symbol:         _Z8fwd_mega4Args.kd
    .uniform_work_group_size: 1
    .uses_dynamic_stack: false
    .vgpr_count:     256
    .vgpr_spill_count: 0
    .wavefront_size: 64
